# GEMM K loop: per-segment s_setprio flips removed, one static s_setprio 1 for waves 4-7 before the loop (reset after it)
# speedup vs baseline: 1.0062x; 1.0062x over previous
; #define PG8_STAGE(bufoff, gbase, voff) do { _Pragma("unroll") for (int _i = 0; _i < 2; ++_i) \
;         __builtin_amdgcn_global_load_lds((const unsigned*)((const char*)(gbase) + (voff)[_i]), (LAS unsigned*)(lds + (bufoff) + ldsw + _i * 8192), 16, 0, 0); } while (0)
; #define PG8_LDA(dst, b, h) do { _Pragma("unroll") for (int m = 0; m < 4; ++m) _Pragma("unroll") for (int k = 0; k < 2; ++k) dst[m][k] = *(const LAS bf16x8*)(lds + PG8_SA(b, h) + aoff + m * 2048 + k * 1024); } while (0)
; #define PG8_LDB(dst, b, h) do { _Pragma("unroll") for (int n = 0; n < 2; ++n) _Pragma("unroll") for (int k = 0; k < 2; ++k) dst[n][k] = *(const LAS bf16x8*)(lds + PG8_SB(b, h) + boff + n * 2048 + k * 1024); } while (0)
; #define PG8_MMA(ai, bj, At, Bt) do { __builtin_amdgcn_s_setprio(1); _Pragma("unroll") for (int m = 0; m < 4; ++m) _Pragma("unroll") for (int n = 0; n < 2; ++n) _Pragma("unroll") for (int k = 0; k < 2; ++k) \
;         acc[ai][bj][m][n] = __builtin_amdgcn_mfma_f32_16x16x32_bf16(Bt[n][k], At[m][k], acc[ai][bj][m][n], 0, 0, 0); __builtin_amdgcn_s_setprio(0); } while (0)
; DI void gemm_phase(LAS unsigned char* lds, const GemmD g, const int kind, const int l) {
;     ...
;         const bool has_next = unit_at(g, ui + 1, G, c, nxt);
;         const char* nA = has_next ? (const char*)g.A + (size_t)nxt.pm * tstepA + (size_t)nxt.pn * pnA : cA; const char* nB = has_next ? (const char*)g.Bt + (size_t)nxt.pn * tstepB : cB;
;         for (int t = 0; t < nt; t += 2) {
;             const bool last = (t == nt - 2);
;             const char* a1 = cA + (size_t)(t + 1) * kstep;
;             const char* a2 = last ? nA : cA + (size_t)(t + 2) * kstep; const char* b2 = last ? nB : cB + (size_t)(t + 2) * kstep;
;             const char* a3 = a2 + kstep; const char* b3 = b2 + kstep;
;             PG8_LDB(B0, 0, 0); PG8_LDB(B1, 0, 1); PG8_SCHED; PG8_LDA(At, 0, 0); PG8_STAGE(PG8_SA(1, 1), a1 + hstepA, voffA);
;             PG8_WAIT_V(8); PG8_WAIT_L(0); PG8_BAR; PG8_MMA(0, 0, At, B0); PG8_MMA(0, 1, At, B1); PG8_BAR; PG8_SCHED;
;     ...
; #pragma unroll
;         for (int a = 0; a < 2; ++a)
; #pragma unroll
;             for (int b = 0; b < 2; ++b)
; #pragma unroll
;                 for (int m = 0; m < 4; ++m)
; #pragma unroll
;                     for (int n = 0; n < 2; ++n) acc[a][b][m][n] = (f32x4){0.f, 0.f, 0.f, 0.f};
;         cur = nxt; cA = nA; cB = nB; ++ui;
.LBB0_253:
	s_add_u32 s4, s4, 0x80
	s_addc_u32 s5, s5, 0
	s_add_u32 s8, s6, 0x100
	v_mov_b32_e32 v0, 0
	s_addc_u32 s9, s7, 0
	s_mov_b32 s6, 0
	v_mov_b32_e32 v1, v0
	v_mov_b32_e32 v2, v0
	v_mov_b32_e32 v3, v0
	v_mov_b32_e32 v4, v0
	v_mov_b32_e32 v5, v0
	v_mov_b32_e32 v6, v0
	v_mov_b32_e32 v7, v0
	v_mov_b32_e32 v16, v0
	v_mov_b32_e32 v17, v0
	v_mov_b32_e32 v18, v0
	v_mov_b32_e32 v19, v0
	v_mov_b32_e32 v20, v0
	v_mov_b32_e32 v21, v0
	v_mov_b32_e32 v22, v0
	v_mov_b32_e32 v23, v0
	v_mov_b32_e32 v34, v0
	v_mov_b32_e32 v35, v0
	v_mov_b32_e32 v36, v0
	v_mov_b32_e32 v37, v0
	v_mov_b32_e32 v38, v0
	v_mov_b32_e32 v39, v0
	v_mov_b32_e32 v40, v0
	v_mov_b32_e32 v41, v0
	v_mov_b32_e32 v50, v0
	v_mov_b32_e32 v51, v0
	v_mov_b32_e32 v52, v0
	v_mov_b32_e32 v53, v0
	v_mov_b32_e32 v54, v0
	v_mov_b32_e32 v55, v0
	v_mov_b32_e32 v56, v0
	v_mov_b32_e32 v57, v0
	v_mov_b32_e32 v8, v0
	v_mov_b32_e32 v9, v0
	v_mov_b32_e32 v10, v0
	v_mov_b32_e32 v11, v0
	v_mov_b32_e32 v12, v0
	v_mov_b32_e32 v13, v0
	v_mov_b32_e32 v14, v0
	v_mov_b32_e32 v15, v0
	v_mov_b32_e32 v26, v0
	v_mov_b32_e32 v27, v0
	v_mov_b32_e32 v28, v0
	v_mov_b32_e32 v29, v0
	v_mov_b32_e32 v30, v0
	v_mov_b32_e32 v31, v0
	v_mov_b32_e32 v32, v0
	v_mov_b32_e32 v33, v0
	v_mov_b32_e32 v42, v0
	v_mov_b32_e32 v43, v0
	v_mov_b32_e32 v44, v0
	v_mov_b32_e32 v45, v0
	v_mov_b32_e32 v46, v0
	v_mov_b32_e32 v47, v0
	v_mov_b32_e32 v48, v0
	v_mov_b32_e32 v49, v0
	v_mov_b32_e32 v58, v0
	v_mov_b32_e32 v59, v0
	v_mov_b32_e32 v60, v0
	v_mov_b32_e32 v61, v0
	v_mov_b32_e32 v62, v0
	v_mov_b32_e32 v63, v0
	v_mov_b32_e32 v64, v0
	v_mov_b32_e32 v65, v0
	v_mov_b32_e32 v66, v0
	v_mov_b32_e32 v67, v0
	v_mov_b32_e32 v68, v0
	v_mov_b32_e32 v69, v0
	v_mov_b32_e32 v70, v0
	v_mov_b32_e32 v71, v0
	v_mov_b32_e32 v72, v0
	v_mov_b32_e32 v73, v0
	v_mov_b32_e32 v82, v0
	v_mov_b32_e32 v83, v0
	v_mov_b32_e32 v84, v0
	v_mov_b32_e32 v85, v0
	v_mov_b32_e32 v86, v0
	v_mov_b32_e32 v87, v0
	v_mov_b32_e32 v88, v0
	v_mov_b32_e32 v89, v0
	v_mov_b32_e32 v98, v0
	v_mov_b32_e32 v99, v0
	v_mov_b32_e32 v100, v0
	v_mov_b32_e32 v101, v0
	v_mov_b32_e32 v102, v0
	v_mov_b32_e32 v103, v0
	v_mov_b32_e32 v104, v0
	v_mov_b32_e32 v105, v0
	v_mov_b32_e32 v114, v0
	v_mov_b32_e32 v115, v0
	v_mov_b32_e32 v116, v0
	v_mov_b32_e32 v117, v0
	v_mov_b32_e32 v118, v0
	v_mov_b32_e32 v119, v0
	v_mov_b32_e32 v120, v0
	v_mov_b32_e32 v121, v0
	v_mov_b32_e32 v74, v0
	v_mov_b32_e32 v75, v0
	v_mov_b32_e32 v76, v0
	v_mov_b32_e32 v77, v0
	v_mov_b32_e32 v78, v0
	v_mov_b32_e32 v79, v0
	v_mov_b32_e32 v80, v0
	v_mov_b32_e32 v81, v0
	v_mov_b32_e32 v90, v0
	v_mov_b32_e32 v91, v0
	v_mov_b32_e32 v92, v0
	v_mov_b32_e32 v93, v0
	v_mov_b32_e32 v94, v0
	v_mov_b32_e32 v95, v0
	v_mov_b32_e32 v96, v0
	v_mov_b32_e32 v97, v0
	v_mov_b32_e32 v106, v0
	v_mov_b32_e32 v107, v0
	v_mov_b32_e32 v108, v0
	v_mov_b32_e32 v109, v0
	v_mov_b32_e32 v110, v0
	v_mov_b32_e32 v111, v0
	v_mov_b32_e32 v112, v0
	v_mov_b32_e32 v113, v0
	v_mov_b32_e32 v122, v0
	v_mov_b32_e32 v123, v0
	v_mov_b32_e32 v124, v0
	v_mov_b32_e32 v125, v0
	v_mov_b32_e32 v126, v0
	v_mov_b32_e32 v127, v0
	v_mov_b32_e32 v128, v0
	v_mov_b32_e32 v129, v0
	v_readlane_b32 s10, v255, 46
	v_readlane_b32 s11, v255, 47
	s_nop 3
	s_cmp_eq_u64 s[10:11], 0
	s_cbranch_scc0 .Lprio_done
	s_setprio 1
.Lprio_done:
.LBB0_254:
	s_add_i32 s10, s6, 2
	s_add_u32 s11, s4, 0x80
	s_addc_u32 s7, s5, 0
	s_add_i32 s14, 0, 0x10000
	s_cmp_eq_u32 s50, s6
	s_cselect_b32 s7, s75, s7
	s_cselect_b32 s6, s74, s11
	v_add_u32_e32 v24, s14, v214
	s_cselect_b32 s13, s77, s9
	s_cselect_b32 s12, s76, s8
	s_add_i32 s11, 0, 0x14000
	ds_read_b128 v[130:133], v24
	ds_read_b128 v[134:137], v24 offset:1024
	ds_read_b128 v[138:141], v24 offset:2048
	ds_read_b128 v[142:145], v24 offset:3072
	v_add_u32_e32 v24, s11, v214
	ds_read_b128 v[146:149], v24
	ds_read_b128 v[150:153], v24 offset:1024
	ds_read_b128 v[154:157], v24 offset:2048
	ds_read_b128 v[172:175], v24 offset:3072
	v_lshl_add_u64 v[240:241], s[4:5], 0, v[168:169]
	s_add_i32 m0, s67, 0xc000
	ds_read_b128 v[176:179], v215
	ds_read_b128 v[180:183], v215 offset:1024
	ds_read_b128 v[216:219], v215 offset:2048
	ds_read_b128 v[220:223], v215 offset:3072
	ds_read_b128 v[224:227], v215 offset:4096
	ds_read_b128 v[228:231], v215 offset:5120
	ds_read_b128 v[232:235], v215 offset:6144
	ds_read_b128 v[236:239], v215 offset:7168
	global_load_lds_dwordx4 v[240:241], off
	v_lshl_add_u64 v[240:241], s[4:5], 0, v[170:171]
	s_add_i32 m0, s67, 0xe000
	s_nop 0
	global_load_lds_dwordx4 v[240:241], off
	s_waitcnt vmcnt(8)
	s_waitcnt lgkmcnt(0)
	s_barrier
; #define PG8_STAGE(bufoff, gbase, voff) do { _Pragma("unroll") for (int _i = 0; _i < 2; ++_i) \
;         __builtin_amdgcn_global_load_lds((const unsigned*)((const char*)(gbase) + (voff)[_i]), (LAS unsigned*)(lds + (bufoff) + ldsw + _i * 8192), 16, 0, 0); } while (0)
; #define PG8_LDA(dst, b, h) do { _Pragma("unroll") for (int m = 0; m < 4; ++m) _Pragma("unroll") for (int k = 0; k < 2; ++k) dst[m][k] = *(const LAS bf16x8*)(lds + PG8_SA(b, h) + aoff + m * 2048 + k * 1024); } while (0)
; #define PG8_MMA(ai, bj, At, Bt) do { __builtin_amdgcn_s_setprio(1); _Pragma("unroll") for (int m = 0; m < 4; ++m) _Pragma("unroll") for (int n = 0; n < 2; ++n) _Pragma("unroll") for (int k = 0; k < 2; ++k) \
;         acc[ai][bj][m][n] = __builtin_amdgcn_mfma_f32_16x16x32_bf16(Bt[n][k], At[m][k], acc[ai][bj][m][n], 0, 0, 0); __builtin_amdgcn_s_setprio(0); } while (0)
; #define PG8_WAIT_V(n) asm volatile("s_waitcnt vmcnt(" #n ")" ::: "memory")
; #define PG8_WAIT_L(n) asm volatile("s_waitcnt lgkmcnt(" #n ")" ::: "memory")
; #define PG8_BAR __builtin_amdgcn_s_barrier()
; #define PG8_SCHED __builtin_amdgcn_sched_barrier(0)
; DI void gemm_phase(LAS unsigned char* lds, const GemmD g, const int kind, const int l) {
;     ...
;             PG8_WAIT_V(8); PG8_WAIT_L(0); PG8_BAR; PG8_MMA(0, 0, At, B0); PG8_MMA(0, 1, At, B1); PG8_BAR; PG8_SCHED;
;             PG8_LDA(At, 0, 1); PG8_STAGE(PG8_SB(0, 0), b2, voffB); PG8_STAGE(PG8_SB(0, 1), b2 + hstepB, voffB); PG8_STAGE(PG8_SA(0, 0), a2, voffA);
;             PG8_WAIT_V(8); PG8_WAIT_L(0); PG8_BAR; PG8_MMA(1, 0, At, B0); PG8_MMA(1, 1, At, B1); PG8_BAR; PG8_SCHED;
	s_waitcnt lgkmcnt(0)
	v_mfma_f32_16x16x32_bf16 v[126:129], v[130:133], v[176:179], v[126:129]
	v_mfma_f32_16x16x32_bf16 v[122:125], v[138:141], v[176:179], v[122:125]
	v_mfma_f32_16x16x32_bf16 v[110:113], v[130:133], v[216:219], v[110:113]
	v_mfma_f32_16x16x32_bf16 v[106:109], v[138:141], v[216:219], v[106:109]
	v_mfma_f32_16x16x32_bf16 v[94:97], v[130:133], v[224:227], v[94:97]
	v_mfma_f32_16x16x32_bf16 v[90:93], v[138:141], v[224:227], v[90:93]
	v_mfma_f32_16x16x32_bf16 v[78:81], v[130:133], v[232:235], v[78:81]
	v_mfma_f32_16x16x32_bf16 v[74:77], v[138:141], v[232:235], v[74:77]
	v_mfma_f32_16x16x32_bf16 v[126:129], v[134:137], v[180:183], v[126:129]
	v_mfma_f32_16x16x32_bf16 v[122:125], v[142:145], v[180:183], v[122:125]
	v_mfma_f32_16x16x32_bf16 v[110:113], v[134:137], v[220:223], v[110:113]
	v_mfma_f32_16x16x32_bf16 v[106:109], v[142:145], v[220:223], v[106:109]
	v_mfma_f32_16x16x32_bf16 v[94:97], v[134:137], v[228:231], v[94:97]
	v_mfma_f32_16x16x32_bf16 v[90:93], v[142:145], v[228:231], v[90:93]
	v_mfma_f32_16x16x32_bf16 v[78:81], v[134:137], v[236:239], v[78:81]
	v_mfma_f32_16x16x32_bf16 v[74:77], v[142:145], v[236:239], v[74:77]
	v_mfma_f32_16x16x32_bf16 v[118:121], v[146:149], v[176:179], v[118:121]
	v_mfma_f32_16x16x32_bf16 v[114:117], v[154:157], v[176:179], v[114:117]
	v_mfma_f32_16x16x32_bf16 v[102:105], v[146:149], v[216:219], v[102:105]
	v_mfma_f32_16x16x32_bf16 v[98:101], v[154:157], v[216:219], v[98:101]
	v_mfma_f32_16x16x32_bf16 v[86:89], v[146:149], v[224:227], v[86:89]
	v_mfma_f32_16x16x32_bf16 v[82:85], v[154:157], v[224:227], v[82:85]
	v_mfma_f32_16x16x32_bf16 v[70:73], v[146:149], v[232:235], v[70:73]
	v_mfma_f32_16x16x32_bf16 v[66:69], v[154:157], v[232:235], v[66:69]
	v_mfma_f32_16x16x32_bf16 v[118:121], v[150:153], v[180:183], v[118:121]
	v_mfma_f32_16x16x32_bf16 v[114:117], v[172:175], v[180:183], v[114:117]
	v_mfma_f32_16x16x32_bf16 v[102:105], v[150:153], v[220:223], v[102:105]
	v_mfma_f32_16x16x32_bf16 v[98:101], v[172:175], v[220:223], v[98:101]
	v_mfma_f32_16x16x32_bf16 v[86:89], v[150:153], v[228:231], v[86:89]
	v_mfma_f32_16x16x32_bf16 v[82:85], v[172:175], v[228:231], v[82:85]
	v_mfma_f32_16x16x32_bf16 v[70:73], v[150:153], v[236:239], v[70:73]
	v_mfma_f32_16x16x32_bf16 v[66:69], v[172:175], v[236:239], v[66:69]
	s_barrier
	s_add_i32 s14, s14, s66
	v_lshl_add_u64 v[240:241], s[12:13], 0, v[160:161]
	s_mov_b32 m0, s14
	ds_read_b128 v[176:179], v215 offset:16384
	ds_read_b128 v[180:183], v215 offset:17408
	ds_read_b128 v[216:219], v215 offset:18432
	ds_read_b128 v[220:223], v215 offset:19456
	ds_read_b128 v[224:227], v215 offset:20480
	ds_read_b128 v[228:231], v215 offset:21504
	ds_read_b128 v[232:235], v215 offset:22528
	ds_read_b128 v[236:239], v215 offset:23552
	global_load_lds_dwordx4 v[240:241], off
	s_add_i32 m0, s14, 0x2000
	v_lshl_add_u64 v[242:243], s[12:13], 0, v[164:165]
	s_add_u32 s12, s12, s54
	s_addc_u32 s13, s13, s55
	s_add_i32 s11, s11, s66
	global_load_lds_dwordx4 v[242:243], off
	v_lshl_add_u64 v[244:245], s[12:13], 0, v[160:161]
	s_mov_b32 m0, s11
	v_lshl_add_u64 v[246:247], s[12:13], 0, v[164:165]
	global_load_lds_dwordx4 v[244:245], off
	s_add_i32 m0, s11, 0x2000
	v_lshl_add_u64 v[248:249], s[6:7], 0, v[158:159]
	global_load_lds_dwordx4 v[246:247], off
	s_mov_b32 m0, s67
	v_lshl_add_u64 v[250:251], s[6:7], 0, v[162:163]
	global_load_lds_dwordx4 v[248:249], off
	s_mov_b32 m0, s25
	s_nop 0
	global_load_lds_dwordx4 v[250:251], off
	s_waitcnt vmcnt(8)
	s_waitcnt lgkmcnt(0)
	s_barrier
	s_waitcnt lgkmcnt(0)
	v_mfma_f32_16x16x32_bf16 v[62:65], v[130:133], v[176:179], v[62:65]
	v_mfma_f32_16x16x32_bf16 v[58:61], v[138:141], v[176:179], v[58:61]
	v_mfma_f32_16x16x32_bf16 v[46:49], v[130:133], v[216:219], v[46:49]
	v_mfma_f32_16x16x32_bf16 v[42:45], v[138:141], v[216:219], v[42:45]
	v_mfma_f32_16x16x32_bf16 v[30:33], v[130:133], v[224:227], v[30:33]
	v_mfma_f32_16x16x32_bf16 v[26:29], v[138:141], v[224:227], v[26:29]
	v_mfma_f32_16x16x32_bf16 v[12:15], v[130:133], v[232:235], v[12:15]
	v_mfma_f32_16x16x32_bf16 v[8:11], v[138:141], v[232:235], v[8:11]
	v_mfma_f32_16x16x32_bf16 v[62:65], v[134:137], v[180:183], v[62:65]
	v_mfma_f32_16x16x32_bf16 v[58:61], v[142:145], v[180:183], v[58:61]
	v_mfma_f32_16x16x32_bf16 v[46:49], v[134:137], v[220:223], v[46:49]
	v_mfma_f32_16x16x32_bf16 v[42:45], v[142:145], v[220:223], v[42:45]
	v_mfma_f32_16x16x32_bf16 v[30:33], v[134:137], v[228:231], v[30:33]
	v_mfma_f32_16x16x32_bf16 v[26:29], v[142:145], v[228:231], v[26:29]
	v_mfma_f32_16x16x32_bf16 v[12:15], v[134:137], v[236:239], v[12:15]
	v_mfma_f32_16x16x32_bf16 v[8:11], v[142:145], v[236:239], v[8:11]
	v_mfma_f32_16x16x32_bf16 v[54:57], v[146:149], v[176:179], v[54:57]
	v_mfma_f32_16x16x32_bf16 v[50:53], v[154:157], v[176:179], v[50:53]
	v_mfma_f32_16x16x32_bf16 v[38:41], v[146:149], v[216:219], v[38:41]
	v_mfma_f32_16x16x32_bf16 v[34:37], v[154:157], v[216:219], v[34:37]
	v_mfma_f32_16x16x32_bf16 v[20:23], v[146:149], v[224:227], v[20:23]
	v_mfma_f32_16x16x32_bf16 v[16:19], v[154:157], v[224:227], v[16:19]
	v_mfma_f32_16x16x32_bf16 v[4:7], v[146:149], v[232:235], v[4:7]
	v_mfma_f32_16x16x32_bf16 v[0:3], v[154:157], v[232:235], v[0:3]
	v_mfma_f32_16x16x32_bf16 v[54:57], v[150:153], v[180:183], v[54:57]
	v_mfma_f32_16x16x32_bf16 v[50:53], v[172:175], v[180:183], v[50:53]
	v_mfma_f32_16x16x32_bf16 v[38:41], v[150:153], v[220:223], v[38:41]
	v_mfma_f32_16x16x32_bf16 v[34:37], v[172:175], v[220:223], v[34:37]
	v_mfma_f32_16x16x32_bf16 v[20:23], v[150:153], v[228:231], v[20:23]
	v_mfma_f32_16x16x32_bf16 v[16:19], v[172:175], v[228:231], v[16:19]
	v_mfma_f32_16x16x32_bf16 v[4:7], v[150:153], v[236:239], v[4:7]
	v_mfma_f32_16x16x32_bf16 v[0:3], v[172:175], v[236:239], v[0:3]
	s_barrier
; #define PG8_STAGE(bufoff, gbase, voff) do { _Pragma("unroll") for (int _i = 0; _i < 2; ++_i) \
;         __builtin_amdgcn_global_load_lds((const unsigned*)((const char*)(gbase) + (voff)[_i]), (LAS unsigned*)(lds + (bufoff) + ldsw + _i * 8192), 16, 0, 0); } while (0)
; #define PG8_LDA(dst, b, h) do { _Pragma("unroll") for (int m = 0; m < 4; ++m) _Pragma("unroll") for (int k = 0; k < 2; ++k) dst[m][k] = *(const LAS bf16x8*)(lds + PG8_SA(b, h) + aoff + m * 2048 + k * 1024); } while (0)
; #define PG8_LDB(dst, b, h) do { _Pragma("unroll") for (int n = 0; n < 2; ++n) _Pragma("unroll") for (int k = 0; k < 2; ++k) dst[n][k] = *(const LAS bf16x8*)(lds + PG8_SB(b, h) + boff + n * 2048 + k * 1024); } while (0)
; #define PG8_MMA(ai, bj, At, Bt) do { __builtin_amdgcn_s_setprio(1); _Pragma("unroll") for (int m = 0; m < 4; ++m) _Pragma("unroll") for (int n = 0; n < 2; ++n) _Pragma("unroll") for (int k = 0; k < 2; ++k) \
;         acc[ai][bj][m][n] = __builtin_amdgcn_mfma_f32_16x16x32_bf16(Bt[n][k], At[m][k], acc[ai][bj][m][n], 0, 0, 0); __builtin_amdgcn_s_setprio(0); } while (0)
; #define PG8_WAIT_V(n) asm volatile("s_waitcnt vmcnt(" #n ")" ::: "memory")
; #define PG8_WAIT_L(n) asm volatile("s_waitcnt lgkmcnt(" #n ")" ::: "memory")
; #define PG8_BAR __builtin_amdgcn_s_barrier()
; #define PG8_SCHED __builtin_amdgcn_sched_barrier(0)
; DI void gemm_phase(LAS unsigned char* lds, const GemmD g, const int kind, const int l) {
;     ...
;             PG8_LDB(B0, 1, 0); PG8_LDB(B1, 1, 1); PG8_SCHED; PG8_LDA(At, 1, 0); PG8_STAGE(PG8_SA(0, 1), a2 + hstepA, voffA);
;             PG8_WAIT_V(8); PG8_WAIT_L(0); PG8_BAR; PG8_MMA(0, 0, At, B0); PG8_MMA(0, 1, At, B1); PG8_BAR; PG8_SCHED;
	s_add_i32 s11, 0, 0x18000
	v_add_u32_e32 v24, s11, v214
	s_add_i32 s12, 0, 0x1c000
	ds_read_b128 v[130:133], v24
	ds_read_b128 v[134:137], v24 offset:1024
	ds_read_b128 v[138:141], v24 offset:2048
	ds_read_b128 v[142:145], v24 offset:3072
	v_add_u32_e32 v24, s12, v214
	ds_read_b128 v[146:149], v24
	ds_read_b128 v[150:153], v24 offset:1024
	ds_read_b128 v[154:157], v24 offset:2048
	ds_read_b128 v[172:175], v24 offset:3072
	s_add_u32 s6, s6, s52
	s_addc_u32 s7, s7, s53
	s_mov_b32 m0, s60
	v_lshl_add_u64 v[252:253], s[6:7], 0, v[158:159]
	ds_read_b128 v[176:179], v215 offset:32768
	ds_read_b128 v[180:183], v215 offset:33792
	ds_read_b128 v[216:219], v215 offset:34816
	ds_read_b128 v[220:223], v215 offset:35840
	ds_read_b128 v[224:227], v215 offset:36864
	ds_read_b128 v[228:231], v215 offset:37888
	ds_read_b128 v[232:235], v215 offset:38912
	ds_read_b128 v[236:239], v215 offset:39936
	global_load_lds_dwordx4 v[252:253], off
	v_lshl_add_u64 v[252:253], s[6:7], 0, v[162:163]
	s_mov_b32 m0, s61
	s_nop 0
	global_load_lds_dwordx4 v[252:253], off
	s_waitcnt vmcnt(8)
	s_waitcnt lgkmcnt(0)
	s_barrier
	s_waitcnt lgkmcnt(0)
	v_mfma_f32_16x16x32_bf16 v[126:129], v[130:133], v[176:179], v[126:129]
	v_mfma_f32_16x16x32_bf16 v[122:125], v[138:141], v[176:179], v[122:125]
	v_mfma_f32_16x16x32_bf16 v[110:113], v[130:133], v[216:219], v[110:113]
	v_mfma_f32_16x16x32_bf16 v[106:109], v[138:141], v[216:219], v[106:109]
	v_mfma_f32_16x16x32_bf16 v[94:97], v[130:133], v[224:227], v[94:97]
	v_mfma_f32_16x16x32_bf16 v[90:93], v[138:141], v[224:227], v[90:93]
	v_mfma_f32_16x16x32_bf16 v[78:81], v[130:133], v[232:235], v[78:81]
	v_mfma_f32_16x16x32_bf16 v[74:77], v[138:141], v[232:235], v[74:77]
	v_mfma_f32_16x16x32_bf16 v[126:129], v[134:137], v[180:183], v[126:129]
	v_mfma_f32_16x16x32_bf16 v[122:125], v[142:145], v[180:183], v[122:125]
	v_mfma_f32_16x16x32_bf16 v[110:113], v[134:137], v[220:223], v[110:113]
	v_mfma_f32_16x16x32_bf16 v[106:109], v[142:145], v[220:223], v[106:109]
	v_mfma_f32_16x16x32_bf16 v[94:97], v[134:137], v[228:231], v[94:97]
	v_mfma_f32_16x16x32_bf16 v[90:93], v[142:145], v[228:231], v[90:93]
	v_mfma_f32_16x16x32_bf16 v[78:81], v[134:137], v[236:239], v[78:81]
	v_mfma_f32_16x16x32_bf16 v[74:77], v[142:145], v[236:239], v[74:77]
	v_mfma_f32_16x16x32_bf16 v[118:121], v[146:149], v[176:179], v[118:121]
	v_mfma_f32_16x16x32_bf16 v[114:117], v[154:157], v[176:179], v[114:117]
	v_mfma_f32_16x16x32_bf16 v[102:105], v[146:149], v[216:219], v[102:105]
	v_mfma_f32_16x16x32_bf16 v[98:101], v[154:157], v[216:219], v[98:101]
	v_mfma_f32_16x16x32_bf16 v[86:89], v[146:149], v[224:227], v[86:89]
	v_mfma_f32_16x16x32_bf16 v[82:85], v[154:157], v[224:227], v[82:85]
	v_mfma_f32_16x16x32_bf16 v[70:73], v[146:149], v[232:235], v[70:73]
	v_mfma_f32_16x16x32_bf16 v[66:69], v[154:157], v[232:235], v[66:69]
	v_mfma_f32_16x16x32_bf16 v[118:121], v[150:153], v[180:183], v[118:121]
	v_mfma_f32_16x16x32_bf16 v[114:117], v[172:175], v[180:183], v[114:117]
	v_mfma_f32_16x16x32_bf16 v[102:105], v[150:153], v[220:223], v[102:105]
	v_mfma_f32_16x16x32_bf16 v[98:101], v[172:175], v[220:223], v[98:101]
	v_mfma_f32_16x16x32_bf16 v[86:89], v[150:153], v[228:231], v[86:89]
	v_mfma_f32_16x16x32_bf16 v[82:85], v[172:175], v[228:231], v[82:85]
	v_mfma_f32_16x16x32_bf16 v[70:73], v[150:153], v[236:239], v[70:73]
	v_mfma_f32_16x16x32_bf16 v[66:69], v[172:175], v[236:239], v[66:69]
	s_barrier
; #define PG8_STAGE(bufoff, gbase, voff) do { _Pragma("unroll") for (int _i = 0; _i < 2; ++_i) \
;         __builtin_amdgcn_global_load_lds((const unsigned*)((const char*)(gbase) + (voff)[_i]), (LAS unsigned*)(lds + (bufoff) + ldsw + _i * 8192), 16, 0, 0); } while (0)
; #define PG8_LDA(dst, b, h) do { _Pragma("unroll") for (int m = 0; m < 4; ++m) _Pragma("unroll") for (int k = 0; k < 2; ++k) dst[m][k] = *(const LAS bf16x8*)(lds + PG8_SA(b, h) + aoff + m * 2048 + k * 1024); } while (0)
; #define PG8_MMA(ai, bj, At, Bt) do { __builtin_amdgcn_s_setprio(1); _Pragma("unroll") for (int m = 0; m < 4; ++m) _Pragma("unroll") for (int n = 0; n < 2; ++n) _Pragma("unroll") for (int k = 0; k < 2; ++k) \
;         acc[ai][bj][m][n] = __builtin_amdgcn_mfma_f32_16x16x32_bf16(Bt[n][k], At[m][k], acc[ai][bj][m][n], 0, 0, 0); __builtin_amdgcn_s_setprio(0); } while (0)
; #define PG8_WAIT_V(n) asm volatile("s_waitcnt vmcnt(" #n ")" ::: "memory")
; #define PG8_WAIT_L(n) asm volatile("s_waitcnt lgkmcnt(" #n ")" ::: "memory")
; #define PG8_BAR __builtin_amdgcn_s_barrier()
; #define PG8_SCHED __builtin_amdgcn_sched_barrier(0)
; DI void gemm_phase(LAS unsigned char* lds, const GemmD g, const int kind, const int l) {
;     ...
;             PG8_LDA(At, 1, 1); PG8_STAGE(PG8_SB(1, 0), b3, voffB); PG8_STAGE(PG8_SB(1, 1), b3 + hstepB, voffB); PG8_STAGE(PG8_SA(1, 0), a3, voffA);
;             PG8_WAIT_V(8); PG8_WAIT_L(0); PG8_BAR; PG8_MMA(1, 0, At, B0); PG8_MMA(1, 1, At, B1); PG8_BAR; PG8_SCHED;
;         }
;         if (wr == 0) PG8_BAR;
	s_add_i32 s6, s11, s66
	v_lshl_add_u64 v[240:241], v[240:241], 0, s[80:81]
	s_mov_b32 m0, s6
	ds_read_b128 v[176:179], v215 offset:49152
	ds_read_b128 v[180:183], v215 offset:50176
	ds_read_b128 v[216:219], v215 offset:51200
	ds_read_b128 v[220:223], v215 offset:52224
	ds_read_b128 v[224:227], v215 offset:53248
	ds_read_b128 v[228:231], v215 offset:54272
	ds_read_b128 v[232:235], v215 offset:55296
	ds_read_b128 v[236:239], v215 offset:56320
	global_load_lds_dwordx4 v[240:241], off
	v_lshl_add_u64 v[240:241], v[242:243], 0, s[80:81]
	s_add_i32 m0, s6, 0x2000
	s_add_i32 s6, s12, s66
	global_load_lds_dwordx4 v[240:241], off
	v_lshl_add_u64 v[240:241], v[244:245], 0, s[80:81]
	s_mov_b32 m0, s6
	s_nop 0
	global_load_lds_dwordx4 v[240:241], off
	v_lshl_add_u64 v[240:241], v[246:247], 0, s[80:81]
	s_add_i32 m0, s6, 0x2000
	s_nop 0
	global_load_lds_dwordx4 v[240:241], off
	v_lshl_add_u64 v[240:241], v[248:249], 0, s[80:81]
	s_mov_b32 m0, s2
	s_nop 0
	global_load_lds_dwordx4 v[240:241], off
	v_lshl_add_u64 v[240:241], v[250:251], 0, s[80:81]
	s_mov_b32 m0, s82
	s_nop 0
	global_load_lds_dwordx4 v[240:241], off
	s_waitcnt vmcnt(8)
	s_waitcnt lgkmcnt(0)
	s_barrier
	s_waitcnt lgkmcnt(0)
	v_mfma_f32_16x16x32_bf16 v[62:65], v[130:133], v[176:179], v[62:65]
	v_mfma_f32_16x16x32_bf16 v[58:61], v[138:141], v[176:179], v[58:61]
	v_mfma_f32_16x16x32_bf16 v[46:49], v[130:133], v[216:219], v[46:49]
	v_mfma_f32_16x16x32_bf16 v[42:45], v[138:141], v[216:219], v[42:45]
	v_mfma_f32_16x16x32_bf16 v[30:33], v[130:133], v[224:227], v[30:33]
	v_mfma_f32_16x16x32_bf16 v[26:29], v[138:141], v[224:227], v[26:29]
	v_mfma_f32_16x16x32_bf16 v[12:15], v[130:133], v[232:235], v[12:15]
	v_mfma_f32_16x16x32_bf16 v[8:11], v[138:141], v[232:235], v[8:11]
	v_mfma_f32_16x16x32_bf16 v[62:65], v[134:137], v[180:183], v[62:65]
	v_mfma_f32_16x16x32_bf16 v[58:61], v[142:145], v[180:183], v[58:61]
	v_mfma_f32_16x16x32_bf16 v[46:49], v[134:137], v[220:223], v[46:49]
	v_mfma_f32_16x16x32_bf16 v[42:45], v[142:145], v[220:223], v[42:45]
	v_mfma_f32_16x16x32_bf16 v[30:33], v[134:137], v[228:231], v[30:33]
	v_mfma_f32_16x16x32_bf16 v[26:29], v[142:145], v[228:231], v[26:29]
	v_mfma_f32_16x16x32_bf16 v[12:15], v[134:137], v[236:239], v[12:15]
	v_mfma_f32_16x16x32_bf16 v[8:11], v[142:145], v[236:239], v[8:11]
	v_mfma_f32_16x16x32_bf16 v[54:57], v[146:149], v[176:179], v[54:57]
	v_mfma_f32_16x16x32_bf16 v[50:53], v[154:157], v[176:179], v[50:53]
	v_mfma_f32_16x16x32_bf16 v[38:41], v[146:149], v[216:219], v[38:41]
	v_mfma_f32_16x16x32_bf16 v[34:37], v[154:157], v[216:219], v[34:37]
	v_mfma_f32_16x16x32_bf16 v[20:23], v[146:149], v[224:227], v[20:23]
	v_mfma_f32_16x16x32_bf16 v[16:19], v[154:157], v[224:227], v[16:19]
	v_mfma_f32_16x16x32_bf16 v[4:7], v[146:149], v[232:235], v[4:7]
	v_mfma_f32_16x16x32_bf16 v[0:3], v[154:157], v[232:235], v[0:3]
	v_mfma_f32_16x16x32_bf16 v[54:57], v[150:153], v[180:183], v[54:57]
	v_mfma_f32_16x16x32_bf16 v[50:53], v[172:175], v[180:183], v[50:53]
	v_mfma_f32_16x16x32_bf16 v[38:41], v[150:153], v[220:223], v[38:41]
	v_mfma_f32_16x16x32_bf16 v[34:37], v[172:175], v[220:223], v[34:37]
	v_mfma_f32_16x16x32_bf16 v[20:23], v[150:153], v[228:231], v[20:23]
	v_mfma_f32_16x16x32_bf16 v[16:19], v[172:175], v[228:231], v[16:19]
	v_mfma_f32_16x16x32_bf16 v[4:7], v[150:153], v[236:239], v[4:7]
	v_mfma_f32_16x16x32_bf16 v[0:3], v[172:175], v[236:239], v[0:3]
	s_barrier
	s_add_u32 s4, s4, 0x100
	s_addc_u32 s5, s5, 0
	s_add_u32 s8, s8, 0x100
	s_addc_u32 s9, s9, 0
	s_cmp_ge_u32 s10, s83
	s_mov_b32 s6, s10
	s_cbranch_scc0 .LBB0_254
	s_setprio 0
	v_readlane_b32 s4, v255, 46
	v_readlane_b32 s5, v255, 47
	s_and_b64 vcc, exec, s[4:5]
	s_cbranch_vccz .LBB0_257
	s_barrier
